# in_proj rotary epilogue: cos/sin table loads run up to 3 row groups ahead into staging registers, counted vmcnt waits (no per-group exposed round trip)
# speedup vs baseline: 1.0119x; 1.0041x over previous
; __device__ __forceinline__ unsigned cvt_pk_bf16(float lo, float hi) { unsigned r; asm volatile("v_cvt_pk_bf16_f32 %0, %1, %2" : "=v"(r) : "v"(lo), "v"(hi)); return r; }
;     __device__ __forceinline__ void operator()(const AccT& acc, const Unit& u, int wr, int wc, int fr, int fq) const {
;     ...
;         if (region < 2) {
;             const float qs = (region == 0) ? QSCALE : 1.0f;
;             const bool rotl = ((wc & 1) == 0) && (fq < 2);
;             const float sg = (fq == 0) ? -1.0f : 1.0f;
; #pragma unroll
;             for (int ai = 0; ai < 2; ++ai)
; #pragma unroll
;                 for (int m = 0; m < 4; ++m) {
;                     const int row = u.pm * 256 + ai * 128 + wr * 64 + m * 16 + fr;
;                     const f32x4* rt = (const f32x4*)(ROT + (size_t)row * 16);
;                     const f32x4 c0 = rt[0], c1 = rt[1], s0 = rt[2], s1 = rt[3];
; #pragma unroll
;                     for (int bj = 0; bj < 2; ++bj) {
;                         const int col0 = colt + bj * 128 + wc * 32 + 8 * fq;
;                         f32x4 v0 = acc[ai][bj][m][0], v1 = acc[ai][bj][m][1];
;                         f32x4 p0, p1;
; #pragma unroll
;                         for (int e = 0; e < 4; ++e) { p0[e] = __shfl_xor(v0[e], 16); p1[e] = __shfl_xor(v1[e], 16); }
;                         const f32x4 r0 = v0 * c0 + sg * (p0 * s0), r1 = v1 * c1 + sg * (p1 * s1);
;                         v0 = rotl ? r0 : v0; v1 = rotl ? r1 : v1;
;                         v0 = v0 * qs; v1 = v1 * qs;
;                         u32x4 w; w.x = cvt_pk_bf16(v0[0], v0[1]); w.y = cvt_pk_bf16(v0[2], v0[3]); w.z = cvt_pk_bf16(v1[0], v1[1]); w.w = cvt_pk_bf16(v1[2], v1[3]);
;                         *(u32x4*)(PROJ + (size_t)row * PP + col0) = w;
;                     }
;                     if (m & 1) asm volatile("" ::: "memory");
;                 }
.LBB0_324:
	s_and_b64 vcc, exec, s[8:9]
	s_cbranch_vccz .LBB0_323
	v_lshl_add_u32 v154, s92, 8, v163
	v_ashrrev_i32_e32 v155, 31, v154
	v_lshlrev_b64 v[128:129], 6, v[154:155]
	v_lshl_add_u64 v[128:129], s[20:21], 0, v[128:129]
	global_load_dwordx4 v[156:159], v[128:129], off offset:32
	global_load_dwordx4 v[168:171], v[128:129], off offset:48
	global_load_dwordx4 v[172:175], v[128:129], off
	global_load_dwordx4 v[176:179], v[128:129], off offset:16
	v_or_b32_e32 v232, 16, v154
	v_ashrrev_i32_e32 v233, 31, v232
	v_lshlrev_b64 v[232:233], 6, v[232:233]
	v_lshl_add_u64 v[232:233], s[20:21], 0, v[232:233]
	global_load_dwordx4 v[196:199], v[232:233], off offset:32
	global_load_dwordx4 v[200:203], v[232:233], off offset:48
	global_load_dwordx4 v[204:207], v[232:233], off
	global_load_dwordx4 v[208:211], v[232:233], off offset:16
	v_or_b32_e32 v232, 32, v154
	v_ashrrev_i32_e32 v233, 31, v232
	v_lshlrev_b64 v[232:233], 6, v[232:233]
	v_lshl_add_u64 v[232:233], s[20:21], 0, v[232:233]
	global_load_dwordx4 v[212:215], v[232:233], off offset:32
	global_load_dwordx4 v[216:219], v[232:233], off offset:48
	global_load_dwordx4 v[220:223], v[232:233], off
	global_load_dwordx4 v[226:229], v[232:233], off offset:16
	v_or_b32_e32 v232, 48, v154
	v_ashrrev_i32_e32 v233, 31, v232
	v_lshlrev_b64 v[232:233], 6, v[232:233]
	v_lshl_add_u64 v[232:233], s[20:21], 0, v[232:233]
	global_load_dwordx4 v[236:239], v[232:233], off offset:32
	global_load_dwordx4 v[240:243], v[232:233], off offset:48
	global_load_dwordx4 v[244:247], v[232:233], off
	global_load_dwordx4 v[248:251], v[232:233], off offset:16
	s_cmp_lt_u32 s91, 4
	v_and_b32_e32 v155, 64, v235
	v_xor_b32_e32 v129, 16, v235
	s_cselect_b64 vcc, -1, 0
	v_mov_b32_e32 v128, 0x3e38aa3b
	v_add_u32_e32 v155, 64, v155
	v_cndmask_b32_e32 v128, 1.0, v128, vcc
	v_cmp_lt_i32_e32 vcc, v129, v155
	v_mov_b64_e32 v[130:131], s[18:19]
	v_ashrrev_i32_e32 v153, 31, v152
	v_cndmask_b32_e32 v129, v235, v129, vcc
	v_lshlrev_b32_e32 v129, 2, v129
	ds_bpermute_b32 v180, v129, v124
	ds_bpermute_b32 v181, v129, v125
	ds_bpermute_b32 v182, v129, v120
	ds_bpermute_b32 v183, v129, v121
	ds_bpermute_b32 v184, v129, v126
	ds_bpermute_b32 v186, v129, v122
	ds_bpermute_b32 v185, v129, v127
	ds_bpermute_b32 v187, v129, v123
	ds_bpermute_b32 v188, v129, v116
	ds_bpermute_b32 v190, v129, v112
	ds_bpermute_b32 v189, v129, v117
	ds_bpermute_b32 v191, v129, v113
	ds_bpermute_b32 v194, v129, v114
	ds_bpermute_b32 v195, v129, v115
	ds_bpermute_b32 v192, v129, v118
	ds_bpermute_b32 v193, v129, v119
	v_mad_i64_i32 v[160:161], s[8:9], v154, s52, v[130:131]
	v_lshlrev_b64 v[152:153], 1, v[152:153]
	v_lshl_add_u64 v[160:161], v[160:161], 0, v[152:153]
	s_waitcnt vmcnt(12) lgkmcnt(0)
	v_pk_mul_f32 v[180:181], v[156:157], v[180:181]
	v_pk_mul_f32 v[184:185], v[158:159], v[184:185]
	v_pk_mul_f32 v[186:187], v[170:171], v[186:187]
	v_pk_mul_f32 v[182:183], v[168:169], v[182:183]
	v_pk_mul_f32 v[156:157], v[156:157], v[188:189]
	v_pk_mul_f32 v[170:171], v[170:171], v[194:195]
	v_pk_mul_f32 v[168:169], v[168:169], v[190:191]
	v_pk_mul_f32 v[180:181], v[144:145], v[180:181]
	v_pk_mul_f32 v[184:185], v[146:147], v[184:185]
	v_pk_mul_f32 v[182:183], v[144:145], v[182:183]
	v_pk_mul_f32 v[186:187], v[146:147], v[186:187]
	v_pk_mul_f32 v[156:157], v[144:145], v[156:157]
	v_pk_mul_f32 v[168:169], v[144:145], v[168:169]
	v_pk_mul_f32 v[170:171], v[146:147], v[170:171]
	v_pk_fma_f32 v[180:181], v[124:125], v[172:173], v[180:181]
	v_pk_mul_f32 v[158:159], v[158:159], v[192:193]
	v_pk_fma_f32 v[184:185], v[126:127], v[174:175], v[184:185]
	v_pk_fma_f32 v[186:187], v[122:123], v[178:179], v[186:187]
	v_pk_fma_f32 v[182:183], v[120:121], v[176:177], v[182:183]
	v_pk_fma_f32 v[156:157], v[116:117], v[172:173], v[156:157]
	v_pk_fma_f32 v[170:171], v[114:115], v[178:179], v[170:171]
	v_pk_fma_f32 v[168:169], v[112:113], v[176:177], v[168:169]
	v_cndmask_b32_e64 v125, v125, v181, s[4:5]
	v_cndmask_b32_e64 v124, v124, v180, s[4:5]
	v_pk_mul_f32 v[158:159], v[146:147], v[158:159]
	v_cndmask_b32_e64 v127, v127, v185, s[4:5]
	v_cndmask_b32_e64 v126, v126, v184, s[4:5]
	v_cndmask_b32_e64 v123, v123, v187, s[4:5]
	v_cndmask_b32_e64 v122, v122, v186, s[4:5]
	v_cndmask_b32_e64 v121, v121, v183, s[4:5]
	v_cndmask_b32_e64 v120, v120, v182, s[4:5]
	v_cndmask_b32_e64 v117, v117, v157, s[4:5]
	v_cndmask_b32_e64 v116, v116, v156, s[4:5]
	v_cndmask_b32_e64 v115, v115, v171, s[4:5]
	v_cndmask_b32_e64 v114, v114, v170, s[4:5]
	v_cndmask_b32_e64 v157, v113, v169, s[4:5]
	v_cndmask_b32_e64 v156, v112, v168, s[4:5]
	v_pk_mul_f32 v[112:113], v[128:129], v[124:125] op_sel_hi:[0,1]
	v_pk_fma_f32 v[158:159], v[118:119], v[174:175], v[158:159]
	v_pk_mul_f32 v[126:127], v[128:129], v[126:127] op_sel_hi:[0,1]
	v_pk_mul_f32 v[122:123], v[128:129], v[122:123] op_sel_hi:[0,1]
	v_pk_mul_f32 v[120:121], v[128:129], v[120:121] op_sel_hi:[0,1]
	v_pk_mul_f32 v[124:125], v[128:129], v[114:115] op_sel_hi:[0,1]
	v_cvt_pk_bf16_f32 v112, v112, v113
	v_cvt_pk_bf16_f32 v113, v126, v127
	v_cvt_pk_bf16_f32 v114, v120, v121
	v_cvt_pk_bf16_f32 v115, v122, v123
	v_cndmask_b32_e64 v119, v119, v159, s[4:5]
	v_cndmask_b32_e64 v118, v118, v158, s[4:5]
	global_store_dwordx4 v[160:161], v[112:115], off
	v_pk_mul_f32 v[118:119], v[128:129], v[118:119] op_sel_hi:[0,1]
	v_pk_mul_f32 v[116:117], v[128:129], v[116:117] op_sel_hi:[0,1]
	v_pk_mul_f32 v[114:115], v[128:129], v[156:157] op_sel_hi:[0,1]
	v_or_b32_e32 v156, 16, v154
	v_cvt_pk_bf16_f32 v112, v116, v117
	v_cvt_pk_bf16_f32 v113, v118, v119
	v_ashrrev_i32_e32 v157, 31, v156
	v_cvt_pk_bf16_f32 v114, v114, v115
	v_cvt_pk_bf16_f32 v115, v124, v125
	global_store_dwordx4 v[160:161], v[112:115], off offset:256
	ds_bpermute_b32 v158, v129, v108
	ds_bpermute_b32 v160, v129, v104
	v_lshlrev_b64 v[112:113], 6, v[156:157]
	v_lshl_add_u64 v[124:125], s[20:21], 0, v[112:113]
	s_waitcnt vmcnt(10)
; __device__ __forceinline__ unsigned cvt_pk_bf16(float lo, float hi) { unsigned r; asm volatile("v_cvt_pk_bf16_f32 %0, %1, %2" : "=v"(r) : "v"(lo), "v"(hi)); return r; }
;     __device__ __forceinline__ void operator()(const AccT& acc, const Unit& u, int wr, int wc, int fr, int fq) const {
;     ...
;                 for (int m = 0; m < 4; ++m) {
;                     const int row = u.pm * 256 + ai * 128 + wr * 64 + m * 16 + fr;
;                     const f32x4* rt = (const f32x4*)(ROT + (size_t)row * 16);
;                     const f32x4 c0 = rt[0], c1 = rt[1], s0 = rt[2], s1 = rt[3];
; #pragma unroll
;                     for (int bj = 0; bj < 2; ++bj) {
;                         const int col0 = colt + bj * 128 + wc * 32 + 8 * fq;
;                         f32x4 v0 = acc[ai][bj][m][0], v1 = acc[ai][bj][m][1];
;                         f32x4 p0, p1;
; #pragma unroll
;                         for (int e = 0; e < 4; ++e) { p0[e] = __shfl_xor(v0[e], 16); p1[e] = __shfl_xor(v1[e], 16); }
;                         const f32x4 r0 = v0 * c0 + sg * (p0 * s0), r1 = v1 * c1 + sg * (p1 * s1);
;                         v0 = rotl ? r0 : v0; v1 = rotl ? r1 : v1;
;                         v0 = v0 * qs; v1 = v1 * qs;
;                         u32x4 w; w.x = cvt_pk_bf16(v0[0], v0[1]); w.y = cvt_pk_bf16(v0[2], v0[3]); w.z = cvt_pk_bf16(v1[0], v1[1]); w.w = cvt_pk_bf16(v1[2], v1[3]);
;                         *(u32x4*)(PROJ + (size_t)row * PP + col0) = w;
;                     }
;                     if (m & 1) asm volatile("" ::: "memory");
;                 }
	s_nop 1
	v_mov_b32_e32 v112, v196
	v_mov_b32_e32 v113, v197
	v_mov_b32_e32 v114, v198
	v_mov_b32_e32 v115, v199
	v_mov_b32_e32 v116, v200
	v_mov_b32_e32 v117, v201
	v_mov_b32_e32 v118, v202
	v_mov_b32_e32 v119, v203
	v_mov_b32_e32 v120, v204
	v_mov_b32_e32 v121, v205
	v_mov_b32_e32 v122, v206
	v_mov_b32_e32 v123, v207
	v_mov_b32_e32 v124, v208
	v_mov_b32_e32 v125, v209
	v_mov_b32_e32 v126, v210
	v_mov_b32_e32 v127, v211
	v_add_u32_e32 v232, 0x80, v154
	v_ashrrev_i32_e32 v233, 31, v232
	v_lshlrev_b64 v[232:233], 6, v[232:233]
	v_lshl_add_u64 v[232:233], s[20:21], 0, v[232:233]
	global_load_dwordx4 v[196:199], v[232:233], off offset:32
	global_load_dwordx4 v[200:203], v[232:233], off offset:48
	global_load_dwordx4 v[204:207], v[232:233], off
	global_load_dwordx4 v[208:211], v[232:233], off offset:16
	s_nop 0
	ds_bpermute_b32 v159, v129, v109
	ds_bpermute_b32 v161, v129, v105
	ds_bpermute_b32 v168, v129, v110
	ds_bpermute_b32 v170, v129, v106
	ds_bpermute_b32 v169, v129, v111
	ds_bpermute_b32 v171, v129, v107
	ds_bpermute_b32 v174, v129, v96
	ds_bpermute_b32 v175, v129, v97
	ds_bpermute_b32 v178, v129, v98
	ds_bpermute_b32 v179, v129, v99
	ds_bpermute_b32 v172, v129, v100
	ds_bpermute_b32 v173, v129, v101
	ds_bpermute_b32 v176, v129, v102
	ds_bpermute_b32 v177, v129, v103
	v_mad_i64_i32 v[156:157], s[8:9], v156, s52, v[130:131]
	v_lshl_add_u64 v[156:157], v[156:157], 0, v[152:153]
	s_waitcnt lgkmcnt(9)
	v_pk_mul_f32 v[168:169], v[114:115], v[168:169]
	v_pk_mul_f32 v[158:159], v[112:113], v[158:159]
	s_waitcnt lgkmcnt(8)
	v_pk_mul_f32 v[170:171], v[118:119], v[170:171]
	v_pk_mul_f32 v[160:161], v[116:117], v[160:161]
	s_waitcnt lgkmcnt(4)
	v_pk_mul_f32 v[118:119], v[118:119], v[178:179]
	v_pk_mul_f32 v[116:117], v[116:117], v[174:175]
	s_waitcnt lgkmcnt(0)
	v_pk_mul_f32 v[114:115], v[114:115], v[176:177]
	v_pk_mul_f32 v[112:113], v[112:113], v[172:173]
	v_pk_mul_f32 v[158:159], v[144:145], v[158:159]
	v_pk_mul_f32 v[168:169], v[146:147], v[168:169]
	v_pk_mul_f32 v[160:161], v[144:145], v[160:161]
	v_pk_mul_f32 v[170:171], v[146:147], v[170:171]
	v_pk_mul_f32 v[116:117], v[144:145], v[116:117]
	v_pk_mul_f32 v[118:119], v[146:147], v[118:119]
	v_pk_mul_f32 v[112:113], v[144:145], v[112:113]
	v_pk_mul_f32 v[114:115], v[146:147], v[114:115]
	v_pk_fma_f32 v[168:169], v[110:111], v[122:123], v[168:169]
	v_pk_fma_f32 v[158:159], v[108:109], v[120:121], v[158:159]
	v_pk_fma_f32 v[170:171], v[106:107], v[126:127], v[170:171]
	v_pk_fma_f32 v[160:161], v[104:105], v[124:125], v[160:161]
	v_pk_fma_f32 v[118:119], v[98:99], v[126:127], v[118:119]
	v_pk_fma_f32 v[116:117], v[96:97], v[124:125], v[116:117]
	v_pk_fma_f32 v[114:115], v[102:103], v[122:123], v[114:115]
	v_pk_fma_f32 v[112:113], v[100:101], v[120:121], v[112:113]
	v_cndmask_b32_e64 v111, v111, v169, s[4:5]
	v_cndmask_b32_e64 v110, v110, v168, s[4:5]
	v_cndmask_b32_e64 v109, v109, v159, s[4:5]
	v_cndmask_b32_e64 v108, v108, v158, s[4:5]
	v_cndmask_b32_e64 v107, v107, v171, s[4:5]
	v_cndmask_b32_e64 v106, v106, v170, s[4:5]
	v_cndmask_b32_e64 v105, v105, v161, s[4:5]
	v_cndmask_b32_e64 v104, v104, v160, s[4:5]
	v_cndmask_b32_e64 v99, v99, v119, s[4:5]
	v_cndmask_b32_e64 v98, v98, v118, s[4:5]
	v_cndmask_b32_e64 v97, v97, v117, s[4:5]
	v_cndmask_b32_e64 v96, v96, v116, s[4:5]
	v_cndmask_b32_e64 v103, v103, v115, s[4:5]
	v_cndmask_b32_e64 v102, v102, v114, s[4:5]
	v_cndmask_b32_e64 v101, v101, v113, s[4:5]
	v_cndmask_b32_e64 v100, v100, v112, s[4:5]
	v_pk_mul_f32 v[110:111], v[128:129], v[110:111] op_sel_hi:[0,1]
	v_pk_mul_f32 v[108:109], v[128:129], v[108:109] op_sel_hi:[0,1]
	v_pk_mul_f32 v[106:107], v[128:129], v[106:107] op_sel_hi:[0,1]
	v_pk_mul_f32 v[104:105], v[128:129], v[104:105] op_sel_hi:[0,1]
	v_pk_mul_f32 v[112:113], v[128:129], v[98:99] op_sel_hi:[0,1]
	v_pk_mul_f32 v[114:115], v[128:129], v[96:97] op_sel_hi:[0,1]
	v_cvt_pk_bf16_f32 v96, v108, v109
	v_cvt_pk_bf16_f32 v97, v110, v111
	v_cvt_pk_bf16_f32 v98, v104, v105
	v_cvt_pk_bf16_f32 v99, v106, v107
	v_pk_mul_f32 v[102:103], v[128:129], v[102:103] op_sel_hi:[0,1]
	v_pk_mul_f32 v[100:101], v[128:129], v[100:101] op_sel_hi:[0,1]
	global_store_dwordx4 v[156:157], v[96:99], off
	ds_bpermute_b32 v116, v129, v92
	ds_bpermute_b32 v118, v129, v88
	v_cvt_pk_bf16_f32 v96, v100, v101
	v_cvt_pk_bf16_f32 v97, v102, v103
	v_cvt_pk_bf16_f32 v98, v114, v115
	v_cvt_pk_bf16_f32 v99, v112, v113
	v_or_b32_e32 v112, 32, v154
	v_ashrrev_i32_e32 v113, 31, v112
	global_store_dwordx4 v[156:157], v[96:99], off offset:256
	ds_bpermute_b32 v117, v129, v93
	ds_bpermute_b32 v119, v129, v89
	v_lshlrev_b64 v[96:97], 6, v[112:113]
	v_lshl_add_u64 v[108:109], s[20:21], 0, v[96:97]
	s_waitcnt vmcnt(12)
	s_nop 1
	v_mov_b32_e32 v96, v212
	v_mov_b32_e32 v97, v213
	v_mov_b32_e32 v98, v214
	v_mov_b32_e32 v99, v215
	v_mov_b32_e32 v100, v216
	v_mov_b32_e32 v101, v217
	v_mov_b32_e32 v102, v218
	v_mov_b32_e32 v103, v219
	v_mov_b32_e32 v104, v220
	v_mov_b32_e32 v105, v221
	v_mov_b32_e32 v106, v222
	v_mov_b32_e32 v107, v223
	v_mov_b32_e32 v108, v226
	v_mov_b32_e32 v109, v227
	v_mov_b32_e32 v110, v228
	v_mov_b32_e32 v111, v229
	v_add_u32_e32 v232, 0x90, v154
	v_ashrrev_i32_e32 v233, 31, v232
	v_lshlrev_b64 v[232:233], 6, v[232:233]
	v_lshl_add_u64 v[232:233], s[20:21], 0, v[232:233]
	global_load_dwordx4 v[212:215], v[232:233], off offset:32
	global_load_dwordx4 v[216:219], v[232:233], off offset:48
	global_load_dwordx4 v[220:223], v[232:233], off
	global_load_dwordx4 v[226:229], v[232:233], off offset:16
	s_nop 0
	ds_bpermute_b32 v120, v129, v94
	ds_bpermute_b32 v121, v129, v95
	ds_bpermute_b32 v126, v129, v80
	ds_bpermute_b32 v127, v129, v81
	ds_bpermute_b32 v122, v129, v90
	ds_bpermute_b32 v123, v129, v91
	ds_bpermute_b32 v124, v129, v84
	ds_bpermute_b32 v125, v129, v85
	ds_bpermute_b32 v156, v129, v86
	ds_bpermute_b32 v158, v129, v82
	ds_bpermute_b32 v157, v129, v87
	ds_bpermute_b32 v159, v129, v83
	v_mad_i64_i32 v[112:113], s[8:9], v112, s52, v[130:131]
	v_or_b32_e32 v114, 48, v154
	v_lshl_add_u64 v[112:113], v[112:113], 0, v[152:153]
	v_ashrrev_i32_e32 v115, 31, v114
	s_waitcnt lgkmcnt(10)
; __device__ __forceinline__ unsigned cvt_pk_bf16(float lo, float hi) { unsigned r; asm volatile("v_cvt_pk_bf16_f32 %0, %1, %2" : "=v"(r) : "v"(lo), "v"(hi)); return r; }
;     __device__ __forceinline__ void operator()(const AccT& acc, const Unit& u, int wr, int wc, int fr, int fq) const {
;     ...
;                 for (int m = 0; m < 4; ++m) {
;                     const int row = u.pm * 256 + ai * 128 + wr * 64 + m * 16 + fr;
;                     const f32x4* rt = (const f32x4*)(ROT + (size_t)row * 16);
;                     const f32x4 c0 = rt[0], c1 = rt[1], s0 = rt[2], s1 = rt[3];
; #pragma unroll
;                     for (int bj = 0; bj < 2; ++bj) {
;                         const int col0 = colt + bj * 128 + wc * 32 + 8 * fq;
;                         f32x4 v0 = acc[ai][bj][m][0], v1 = acc[ai][bj][m][1];
;                         f32x4 p0, p1;
; #pragma unroll
;                         for (int e = 0; e < 4; ++e) { p0[e] = __shfl_xor(v0[e], 16); p1[e] = __shfl_xor(v1[e], 16); }
;                         const f32x4 r0 = v0 * c0 + sg * (p0 * s0), r1 = v1 * c1 + sg * (p1 * s1);
;                         v0 = rotl ? r0 : v0; v1 = rotl ? r1 : v1;
;                         v0 = v0 * qs; v1 = v1 * qs;
;                         u32x4 w; w.x = cvt_pk_bf16(v0[0], v0[1]); w.y = cvt_pk_bf16(v0[2], v0[3]); w.z = cvt_pk_bf16(v1[0], v1[1]); w.w = cvt_pk_bf16(v1[2], v1[3]);
;                         *(u32x4*)(PROJ + (size_t)row * PP + col0) = w;
;                     }
;                     if (m & 1) asm volatile("" ::: "memory");
;                 }
	v_pk_mul_f32 v[120:121], v[98:99], v[120:121]
	v_pk_mul_f32 v[116:117], v[96:97], v[116:117]
	v_pk_mul_f32 v[118:119], v[100:101], v[118:119]
	s_waitcnt lgkmcnt(8)
	v_pk_mul_f32 v[100:101], v[100:101], v[126:127]
	s_waitcnt lgkmcnt(6)
	v_pk_mul_f32 v[122:123], v[102:103], v[122:123]
	s_waitcnt lgkmcnt(1)
	v_pk_mul_f32 v[98:99], v[98:99], v[156:157]
	v_pk_mul_f32 v[96:97], v[96:97], v[124:125]
	s_waitcnt lgkmcnt(0)
	v_pk_mul_f32 v[102:103], v[102:103], v[158:159]
	v_pk_mul_f32 v[116:117], v[144:145], v[116:117]
	v_pk_mul_f32 v[120:121], v[146:147], v[120:121]
	v_pk_mul_f32 v[100:101], v[144:145], v[100:101]
	v_pk_mul_f32 v[118:119], v[144:145], v[118:119]
	v_pk_mul_f32 v[122:123], v[146:147], v[122:123]
	v_pk_mul_f32 v[96:97], v[144:145], v[96:97]
	v_pk_mul_f32 v[98:99], v[146:147], v[98:99]
	v_pk_mul_f32 v[102:103], v[146:147], v[102:103]
	v_pk_fma_f32 v[120:121], v[94:95], v[106:107], v[120:121]
	v_pk_fma_f32 v[116:117], v[92:93], v[104:105], v[116:117]
	v_pk_fma_f32 v[100:101], v[80:81], v[108:109], v[100:101]
	v_pk_fma_f32 v[122:123], v[90:91], v[110:111], v[122:123]
	v_pk_fma_f32 v[118:119], v[88:89], v[108:109], v[118:119]
	v_pk_fma_f32 v[98:99], v[86:87], v[106:107], v[98:99]
	v_pk_fma_f32 v[96:97], v[84:85], v[104:105], v[96:97]
	v_pk_fma_f32 v[102:103], v[82:83], v[110:111], v[102:103]
	v_cndmask_b32_e64 v95, v95, v121, s[4:5]
	v_cndmask_b32_e64 v94, v94, v120, s[4:5]
	v_cndmask_b32_e64 v93, v93, v117, s[4:5]
	v_cndmask_b32_e64 v92, v92, v116, s[4:5]
	v_cndmask_b32_e64 v81, v81, v101, s[4:5]
	v_cndmask_b32_e64 v80, v80, v100, s[4:5]
	v_cndmask_b32_e64 v91, v91, v123, s[4:5]
	v_cndmask_b32_e64 v90, v90, v122, s[4:5]
	v_cndmask_b32_e64 v89, v89, v119, s[4:5]
	v_cndmask_b32_e64 v88, v88, v118, s[4:5]
	v_cndmask_b32_e64 v87, v87, v99, s[4:5]
	v_cndmask_b32_e64 v86, v86, v98, s[4:5]
	v_cndmask_b32_e64 v85, v85, v97, s[4:5]
	v_cndmask_b32_e64 v84, v84, v96, s[4:5]
	v_cndmask_b32_e64 v83, v83, v103, s[4:5]
	v_cndmask_b32_e64 v82, v82, v102, s[4:5]
	v_pk_mul_f32 v[94:95], v[128:129], v[94:95] op_sel_hi:[0,1]
	v_pk_mul_f32 v[92:93], v[128:129], v[92:93] op_sel_hi:[0,1]
	v_pk_mul_f32 v[98:99], v[128:129], v[80:81] op_sel_hi:[0,1]
	v_cvt_pk_bf16_f32 v80, v92, v93
	v_cvt_pk_bf16_f32 v81, v94, v95
	v_pk_mul_f32 v[90:91], v[128:129], v[90:91] op_sel_hi:[0,1]
	v_pk_mul_f32 v[88:89], v[128:129], v[88:89] op_sel_hi:[0,1]
	v_pk_mul_f32 v[86:87], v[128:129], v[86:87] op_sel_hi:[0,1]
	v_pk_mul_f32 v[84:85], v[128:129], v[84:85] op_sel_hi:[0,1]
	v_pk_mul_f32 v[96:97], v[128:129], v[82:83] op_sel_hi:[0,1]
	v_cvt_pk_bf16_f32 v82, v88, v89
	v_cvt_pk_bf16_f32 v83, v90, v91
	global_store_dwordx4 v[112:113], v[80:83], off
	ds_bpermute_b32 v102, v129, v76
	ds_bpermute_b32 v104, v129, v72
	v_cvt_pk_bf16_f32 v80, v84, v85
	v_cvt_pk_bf16_f32 v81, v86, v87
	v_cvt_pk_bf16_f32 v82, v98, v99
	v_cvt_pk_bf16_f32 v83, v96, v97
	global_store_dwordx4 v[112:113], v[80:83], off offset:256
	ds_bpermute_b32 v103, v129, v77
	ds_bpermute_b32 v105, v129, v73
	v_lshlrev_b64 v[80:81], 6, v[114:115]
	v_lshl_add_u64 v[80:81], s[20:21], 0, v[80:81]
	s_waitcnt vmcnt(14)
	s_nop 1
	v_mov_b32_e32 v82, v236
	v_mov_b32_e32 v83, v237
	v_mov_b32_e32 v84, v238
	v_mov_b32_e32 v85, v239
	v_mov_b32_e32 v86, v240
	v_mov_b32_e32 v87, v241
	v_mov_b32_e32 v88, v242
	v_mov_b32_e32 v89, v243
	v_mov_b32_e32 v90, v244
	v_mov_b32_e32 v91, v245
	v_mov_b32_e32 v92, v246
	v_mov_b32_e32 v93, v247
	v_mov_b32_e32 v94, v248
	v_mov_b32_e32 v95, v249
	v_mov_b32_e32 v96, v250
	v_mov_b32_e32 v97, v251
	v_add_u32_e32 v232, 0xa0, v154
	v_ashrrev_i32_e32 v233, 31, v232
	v_lshlrev_b64 v[232:233], 6, v[232:233]
	v_lshl_add_u64 v[232:233], s[20:21], 0, v[232:233]
	global_load_dwordx4 v[236:239], v[232:233], off offset:32
	global_load_dwordx4 v[240:243], v[232:233], off offset:48
	global_load_dwordx4 v[244:247], v[232:233], off
	global_load_dwordx4 v[248:251], v[232:233], off offset:16
	ds_bpermute_b32 v106, v129, v78
	ds_bpermute_b32 v108, v129, v74
	ds_bpermute_b32 v107, v129, v79
	ds_bpermute_b32 v109, v129, v75
	ds_bpermute_b32 v112, v129, v64
	ds_bpermute_b32 v113, v129, v65
	ds_bpermute_b32 v116, v129, v66
	ds_bpermute_b32 v117, v129, v67
	v_mad_i64_i32 v[98:99], s[8:9], v114, s52, v[130:131]
	ds_bpermute_b32 v110, v129, v68
	ds_bpermute_b32 v111, v129, v69
	ds_bpermute_b32 v114, v129, v70
	ds_bpermute_b32 v115, v129, v71
	v_add_u32_e32 v80, 0x80, v154
	v_ashrrev_i32_e32 v81, 31, v80
	v_lshl_add_u64 v[98:99], v[98:99], 0, v[152:153]
	v_lshlrev_b64 v[100:101], 6, v[80:81]
	v_lshl_add_u64 v[100:101], s[20:21], 0, v[100:101]
	s_waitcnt lgkmcnt(9)
	v_pk_mul_f32 v[106:107], v[84:85], v[106:107]
	v_pk_mul_f32 v[102:103], v[82:83], v[102:103]
	s_waitcnt lgkmcnt(8)
	v_pk_mul_f32 v[108:109], v[88:89], v[108:109]
	v_pk_mul_f32 v[104:105], v[86:87], v[104:105]
	s_waitcnt lgkmcnt(4)
	v_pk_mul_f32 v[88:89], v[88:89], v[116:117]
	v_pk_mul_f32 v[86:87], v[86:87], v[112:113]
	s_waitcnt lgkmcnt(0)
; __device__ __forceinline__ unsigned cvt_pk_bf16(float lo, float hi) { unsigned r; asm volatile("v_cvt_pk_bf16_f32 %0, %1, %2" : "=v"(r) : "v"(lo), "v"(hi)); return r; }
;     __device__ __forceinline__ void operator()(const AccT& acc, const Unit& u, int wr, int wc, int fr, int fq) const {
;     ...
;                 for (int m = 0; m < 4; ++m) {
;                     const int row = u.pm * 256 + ai * 128 + wr * 64 + m * 16 + fr;
;                     const f32x4* rt = (const f32x4*)(ROT + (size_t)row * 16);
;                     const f32x4 c0 = rt[0], c1 = rt[1], s0 = rt[2], s1 = rt[3];
; #pragma unroll
;                     for (int bj = 0; bj < 2; ++bj) {
;                         const int col0 = colt + bj * 128 + wc * 32 + 8 * fq;
;                         f32x4 v0 = acc[ai][bj][m][0], v1 = acc[ai][bj][m][1];
;                         f32x4 p0, p1;
; #pragma unroll
;                         for (int e = 0; e < 4; ++e) { p0[e] = __shfl_xor(v0[e], 16); p1[e] = __shfl_xor(v1[e], 16); }
;                         const f32x4 r0 = v0 * c0 + sg * (p0 * s0), r1 = v1 * c1 + sg * (p1 * s1);
;                         v0 = rotl ? r0 : v0; v1 = rotl ? r1 : v1;
;                         v0 = v0 * qs; v1 = v1 * qs;
;                         u32x4 w; w.x = cvt_pk_bf16(v0[0], v0[1]); w.y = cvt_pk_bf16(v0[2], v0[3]); w.z = cvt_pk_bf16(v1[0], v1[1]); w.w = cvt_pk_bf16(v1[2], v1[3]);
;                         *(u32x4*)(PROJ + (size_t)row * PP + col0) = w;
;                     }
;                     if (m & 1) asm volatile("" ::: "memory");
;                 }
	v_pk_mul_f32 v[84:85], v[84:85], v[114:115]
	v_pk_mul_f32 v[82:83], v[82:83], v[110:111]
	v_pk_mul_f32 v[102:103], v[144:145], v[102:103]
	v_pk_mul_f32 v[106:107], v[146:147], v[106:107]
	v_pk_mul_f32 v[104:105], v[144:145], v[104:105]
	v_pk_mul_f32 v[108:109], v[146:147], v[108:109]
	v_pk_mul_f32 v[86:87], v[144:145], v[86:87]
	v_pk_mul_f32 v[88:89], v[146:147], v[88:89]
	v_pk_mul_f32 v[82:83], v[144:145], v[82:83]
	v_pk_mul_f32 v[84:85], v[146:147], v[84:85]
	v_pk_fma_f32 v[106:107], v[78:79], v[92:93], v[106:107]
	v_pk_fma_f32 v[102:103], v[76:77], v[90:91], v[102:103]
	v_pk_fma_f32 v[108:109], v[74:75], v[96:97], v[108:109]
	v_pk_fma_f32 v[104:105], v[72:73], v[94:95], v[104:105]
	v_pk_fma_f32 v[88:89], v[66:67], v[96:97], v[88:89]
	v_pk_fma_f32 v[86:87], v[64:65], v[94:95], v[86:87]
	v_pk_fma_f32 v[84:85], v[70:71], v[92:93], v[84:85]
	v_pk_fma_f32 v[82:83], v[68:69], v[90:91], v[82:83]
	v_cndmask_b32_e64 v79, v79, v107, s[4:5]
	v_cndmask_b32_e64 v78, v78, v106, s[4:5]
	v_cndmask_b32_e64 v77, v77, v103, s[4:5]
	v_cndmask_b32_e64 v76, v76, v102, s[4:5]
	v_cndmask_b32_e64 v75, v75, v109, s[4:5]
	v_cndmask_b32_e64 v74, v74, v108, s[4:5]
	v_cndmask_b32_e64 v73, v73, v105, s[4:5]
	v_cndmask_b32_e64 v72, v72, v104, s[4:5]
	v_cndmask_b32_e64 v67, v67, v89, s[4:5]
	v_cndmask_b32_e64 v66, v66, v88, s[4:5]
	v_cndmask_b32_e64 v65, v65, v87, s[4:5]
	v_cndmask_b32_e64 v64, v64, v86, s[4:5]
	v_cndmask_b32_e64 v71, v71, v85, s[4:5]
	v_cndmask_b32_e64 v70, v70, v84, s[4:5]
	v_cndmask_b32_e64 v69, v69, v83, s[4:5]
	v_cndmask_b32_e64 v68, v68, v82, s[4:5]
	v_pk_mul_f32 v[78:79], v[128:129], v[78:79] op_sel_hi:[0,1]
	v_pk_mul_f32 v[76:77], v[128:129], v[76:77] op_sel_hi:[0,1]
	v_pk_mul_f32 v[74:75], v[128:129], v[74:75] op_sel_hi:[0,1]
	v_pk_mul_f32 v[72:73], v[128:129], v[72:73] op_sel_hi:[0,1]
	v_pk_mul_f32 v[82:83], v[128:129], v[66:67] op_sel_hi:[0,1]
	v_pk_mul_f32 v[84:85], v[128:129], v[64:65] op_sel_hi:[0,1]
	v_cvt_pk_bf16_f32 v64, v76, v77
	v_cvt_pk_bf16_f32 v65, v78, v79
	v_cvt_pk_bf16_f32 v66, v72, v73
	v_cvt_pk_bf16_f32 v67, v74, v75
	v_pk_mul_f32 v[70:71], v[128:129], v[70:71] op_sel_hi:[0,1]
	v_pk_mul_f32 v[68:69], v[128:129], v[68:69] op_sel_hi:[0,1]
	global_store_dwordx4 v[98:99], v[64:67], off
	ds_bpermute_b32 v86, v129, v60
	ds_bpermute_b32 v88, v129, v56
	v_cvt_pk_bf16_f32 v64, v68, v69
	v_cvt_pk_bf16_f32 v65, v70, v71
	v_cvt_pk_bf16_f32 v66, v84, v85
	v_cvt_pk_bf16_f32 v67, v82, v83
	global_store_dwordx4 v[98:99], v[64:67], off offset:256
	s_waitcnt vmcnt(14)
	s_nop 1
	v_mov_b32_e32 v66, v196
	v_mov_b32_e32 v67, v197
	v_mov_b32_e32 v68, v198
	v_mov_b32_e32 v69, v199
	v_mov_b32_e32 v70, v200
	v_mov_b32_e32 v71, v201
	v_mov_b32_e32 v72, v202
	v_mov_b32_e32 v73, v203
	v_mov_b32_e32 v74, v204
	v_mov_b32_e32 v75, v205
	v_mov_b32_e32 v76, v206
	v_mov_b32_e32 v77, v207
	v_mov_b32_e32 v82, v208
	v_mov_b32_e32 v83, v209
	v_mov_b32_e32 v84, v210
	v_mov_b32_e32 v85, v211
	v_add_u32_e32 v232, 0xb0, v154
	v_ashrrev_i32_e32 v233, 31, v232
	v_lshlrev_b64 v[232:233], 6, v[232:233]
	v_lshl_add_u64 v[232:233], s[20:21], 0, v[232:233]
	global_load_dwordx4 v[196:199], v[232:233], off offset:32
	global_load_dwordx4 v[200:203], v[232:233], off offset:48
	global_load_dwordx4 v[204:207], v[232:233], off
	global_load_dwordx4 v[208:211], v[232:233], off offset:16
	ds_bpermute_b32 v87, v129, v61
	ds_bpermute_b32 v89, v129, v57
	ds_bpermute_b32 v90, v129, v62
	ds_bpermute_b32 v92, v129, v58
	ds_bpermute_b32 v91, v129, v63
	ds_bpermute_b32 v93, v129, v59
	ds_bpermute_b32 v96, v129, v48
	ds_bpermute_b32 v97, v129, v49
	ds_bpermute_b32 v100, v129, v50
	ds_bpermute_b32 v101, v129, v51
	ds_bpermute_b32 v94, v129, v52
	ds_bpermute_b32 v95, v129, v53
	ds_bpermute_b32 v98, v129, v54
	ds_bpermute_b32 v99, v129, v55
	v_add_u32_e32 v64, 0x90, v154
	v_mad_i64_i32 v[78:79], s[8:9], v80, s52, v[130:131]
	v_ashrrev_i32_e32 v65, 31, v64
	v_lshl_add_u64 v[78:79], v[78:79], 0, v[152:153]
	v_lshlrev_b64 v[80:81], 6, v[64:65]
	v_lshl_add_u64 v[80:81], s[20:21], 0, v[80:81]
	s_waitcnt lgkmcnt(9)
	v_pk_mul_f32 v[90:91], v[68:69], v[90:91]
	v_pk_mul_f32 v[86:87], v[66:67], v[86:87]
	s_waitcnt lgkmcnt(8)
	v_pk_mul_f32 v[92:93], v[72:73], v[92:93]
	v_pk_mul_f32 v[88:89], v[70:71], v[88:89]
	s_waitcnt lgkmcnt(4)
	v_pk_mul_f32 v[72:73], v[72:73], v[100:101]
	v_pk_mul_f32 v[70:71], v[70:71], v[96:97]
	s_waitcnt lgkmcnt(0)
	v_pk_mul_f32 v[68:69], v[68:69], v[98:99]
	v_pk_mul_f32 v[66:67], v[66:67], v[94:95]
	v_pk_mul_f32 v[86:87], v[144:145], v[86:87]
	v_pk_mul_f32 v[90:91], v[146:147], v[90:91]
	v_pk_mul_f32 v[88:89], v[144:145], v[88:89]
	v_pk_mul_f32 v[92:93], v[146:147], v[92:93]
	v_pk_mul_f32 v[70:71], v[144:145], v[70:71]
	v_pk_mul_f32 v[72:73], v[146:147], v[72:73]
	v_pk_mul_f32 v[66:67], v[144:145], v[66:67]
	v_pk_mul_f32 v[68:69], v[146:147], v[68:69]
	v_pk_fma_f32 v[90:91], v[62:63], v[76:77], v[90:91]
	v_pk_fma_f32 v[86:87], v[60:61], v[74:75], v[86:87]
	v_pk_fma_f32 v[92:93], v[58:59], v[84:85], v[92:93]
	v_pk_fma_f32 v[88:89], v[56:57], v[82:83], v[88:89]
	v_pk_fma_f32 v[72:73], v[50:51], v[84:85], v[72:73]
	v_pk_fma_f32 v[70:71], v[48:49], v[82:83], v[70:71]
	v_pk_fma_f32 v[68:69], v[54:55], v[76:77], v[68:69]
	v_pk_fma_f32 v[66:67], v[52:53], v[74:75], v[66:67]
	v_cndmask_b32_e64 v63, v63, v91, s[4:5]
	v_cndmask_b32_e64 v62, v62, v90, s[4:5]
	v_cndmask_b32_e64 v61, v61, v87, s[4:5]
	v_cndmask_b32_e64 v60, v60, v86, s[4:5]
	v_cndmask_b32_e64 v59, v59, v93, s[4:5]
	v_cndmask_b32_e64 v58, v58, v92, s[4:5]
	v_cndmask_b32_e64 v57, v57, v89, s[4:5]
	v_cndmask_b32_e64 v56, v56, v88, s[4:5]
	v_cndmask_b32_e64 v51, v51, v73, s[4:5]
	v_cndmask_b32_e64 v50, v50, v72, s[4:5]
	v_cndmask_b32_e64 v49, v49, v71, s[4:5]
	v_cndmask_b32_e64 v48, v48, v70, s[4:5]
	v_cndmask_b32_e64 v55, v55, v69, s[4:5]
	v_cndmask_b32_e64 v54, v54, v68, s[4:5]
	v_cndmask_b32_e64 v53, v53, v67, s[4:5]
	v_cndmask_b32_e64 v52, v52, v66, s[4:5]
	v_pk_mul_f32 v[62:63], v[128:129], v[62:63] op_sel_hi:[0,1]
	v_pk_mul_f32 v[60:61], v[128:129], v[60:61] op_sel_hi:[0,1]
	v_pk_mul_f32 v[58:59], v[128:129], v[58:59] op_sel_hi:[0,1]
	v_pk_mul_f32 v[56:57], v[128:129], v[56:57] op_sel_hi:[0,1]
	v_pk_mul_f32 v[66:67], v[128:129], v[50:51] op_sel_hi:[0,1]
	v_pk_mul_f32 v[68:69], v[128:129], v[48:49] op_sel_hi:[0,1]
	v_cvt_pk_bf16_f32 v48, v60, v61
	v_cvt_pk_bf16_f32 v49, v62, v63
	v_cvt_pk_bf16_f32 v50, v56, v57
	v_cvt_pk_bf16_f32 v51, v58, v59
	v_pk_mul_f32 v[54:55], v[128:129], v[54:55] op_sel_hi:[0,1]
	v_pk_mul_f32 v[52:53], v[128:129], v[52:53] op_sel_hi:[0,1]
	global_store_dwordx4 v[78:79], v[48:51], off
	ds_bpermute_b32 v70, v129, v44
	ds_bpermute_b32 v72, v129, v40
	v_cvt_pk_bf16_f32 v48, v52, v53
	v_cvt_pk_bf16_f32 v49, v54, v55
	v_cvt_pk_bf16_f32 v50, v68, v69
	v_cvt_pk_bf16_f32 v51, v66, v67
	global_store_dwordx4 v[78:79], v[48:51], off offset:256
	s_waitcnt vmcnt(14)
; __device__ __forceinline__ unsigned cvt_pk_bf16(float lo, float hi) { unsigned r; asm volatile("v_cvt_pk_bf16_f32 %0, %1, %2" : "=v"(r) : "v"(lo), "v"(hi)); return r; }
;     __device__ __forceinline__ void operator()(const AccT& acc, const Unit& u, int wr, int wc, int fr, int fq) const {
;     ...
;                 for (int m = 0; m < 4; ++m) {
;                     const int row = u.pm * 256 + ai * 128 + wr * 64 + m * 16 + fr;
;                     const f32x4* rt = (const f32x4*)(ROT + (size_t)row * 16);
;                     const f32x4 c0 = rt[0], c1 = rt[1], s0 = rt[2], s1 = rt[3];
; #pragma unroll
;                     for (int bj = 0; bj < 2; ++bj) {
;                         const int col0 = colt + bj * 128 + wc * 32 + 8 * fq;
;                         f32x4 v0 = acc[ai][bj][m][0], v1 = acc[ai][bj][m][1];
;                         f32x4 p0, p1;
; #pragma unroll
;                         for (int e = 0; e < 4; ++e) { p0[e] = __shfl_xor(v0[e], 16); p1[e] = __shfl_xor(v1[e], 16); }
;                         const f32x4 r0 = v0 * c0 + sg * (p0 * s0), r1 = v1 * c1 + sg * (p1 * s1);
;                         v0 = rotl ? r0 : v0; v1 = rotl ? r1 : v1;
;                         v0 = v0 * qs; v1 = v1 * qs;
;                         u32x4 w; w.x = cvt_pk_bf16(v0[0], v0[1]); w.y = cvt_pk_bf16(v0[2], v0[3]); w.z = cvt_pk_bf16(v1[0], v1[1]); w.w = cvt_pk_bf16(v1[2], v1[3]);
;                         *(u32x4*)(PROJ + (size_t)row * PP + col0) = w;
;                     }
;                     if (m & 1) asm volatile("" ::: "memory");
;                 }
	s_nop 1
	v_mov_b32_e32 v50, v212
	v_mov_b32_e32 v51, v213
	v_mov_b32_e32 v52, v214
	v_mov_b32_e32 v53, v215
	v_mov_b32_e32 v54, v216
	v_mov_b32_e32 v55, v217
	v_mov_b32_e32 v56, v218
	v_mov_b32_e32 v57, v219
	v_mov_b32_e32 v58, v220
	v_mov_b32_e32 v59, v221
	v_mov_b32_e32 v60, v222
	v_mov_b32_e32 v61, v223
	v_mov_b32_e32 v66, v226
	v_mov_b32_e32 v67, v227
	v_mov_b32_e32 v68, v228
	v_mov_b32_e32 v69, v229
	s_nop 0
	ds_bpermute_b32 v71, v129, v45
	ds_bpermute_b32 v73, v129, v41
	ds_bpermute_b32 v74, v129, v46
	ds_bpermute_b32 v76, v129, v42
	ds_bpermute_b32 v75, v129, v47
	ds_bpermute_b32 v77, v129, v43
	ds_bpermute_b32 v80, v129, v32
	ds_bpermute_b32 v81, v129, v33
	ds_bpermute_b32 v84, v129, v34
	ds_bpermute_b32 v85, v129, v35
	ds_bpermute_b32 v78, v129, v36
	ds_bpermute_b32 v79, v129, v37
	ds_bpermute_b32 v82, v129, v38
	ds_bpermute_b32 v83, v129, v39
	v_add_u32_e32 v48, 0xa0, v154
	v_mad_i64_i32 v[62:63], s[8:9], v64, s52, v[130:131]
	v_ashrrev_i32_e32 v49, 31, v48
	v_lshl_add_u64 v[62:63], v[62:63], 0, v[152:153]
	v_lshlrev_b64 v[64:65], 6, v[48:49]
	v_lshl_add_u64 v[64:65], s[20:21], 0, v[64:65]
	v_mad_i64_i32 v[48:49], s[8:9], v48, s52, v[130:131]
	v_lshl_add_u64 v[48:49], v[48:49], 0, v[152:153]
	s_waitcnt lgkmcnt(9)
	v_pk_mul_f32 v[74:75], v[52:53], v[74:75]
	v_pk_mul_f32 v[70:71], v[50:51], v[70:71]
	s_waitcnt lgkmcnt(8)
	v_pk_mul_f32 v[76:77], v[56:57], v[76:77]
	v_pk_mul_f32 v[72:73], v[54:55], v[72:73]
	s_waitcnt lgkmcnt(4)
	v_pk_mul_f32 v[56:57], v[56:57], v[84:85]
	v_pk_mul_f32 v[54:55], v[54:55], v[80:81]
	s_waitcnt lgkmcnt(0)
	v_pk_mul_f32 v[52:53], v[52:53], v[82:83]
	v_pk_mul_f32 v[50:51], v[50:51], v[78:79]
	v_pk_mul_f32 v[70:71], v[144:145], v[70:71]
	v_pk_mul_f32 v[74:75], v[146:147], v[74:75]
	v_pk_mul_f32 v[72:73], v[144:145], v[72:73]
	v_pk_mul_f32 v[76:77], v[146:147], v[76:77]
	v_pk_mul_f32 v[54:55], v[144:145], v[54:55]
	v_pk_mul_f32 v[56:57], v[146:147], v[56:57]
	v_pk_mul_f32 v[50:51], v[144:145], v[50:51]
	v_pk_mul_f32 v[52:53], v[146:147], v[52:53]
	v_pk_fma_f32 v[74:75], v[46:47], v[60:61], v[74:75]
	v_pk_fma_f32 v[70:71], v[44:45], v[58:59], v[70:71]
	v_pk_fma_f32 v[76:77], v[42:43], v[68:69], v[76:77]
	v_pk_fma_f32 v[72:73], v[40:41], v[66:67], v[72:73]
	v_pk_fma_f32 v[56:57], v[34:35], v[68:69], v[56:57]
	v_pk_fma_f32 v[54:55], v[32:33], v[66:67], v[54:55]
	v_pk_fma_f32 v[52:53], v[38:39], v[60:61], v[52:53]
	v_pk_fma_f32 v[50:51], v[36:37], v[58:59], v[50:51]
	v_cndmask_b32_e64 v47, v47, v75, s[4:5]
	v_cndmask_b32_e64 v46, v46, v74, s[4:5]
	v_cndmask_b32_e64 v45, v45, v71, s[4:5]
	v_cndmask_b32_e64 v44, v44, v70, s[4:5]
	v_cndmask_b32_e64 v43, v43, v77, s[4:5]
	v_cndmask_b32_e64 v42, v42, v76, s[4:5]
	v_cndmask_b32_e64 v41, v41, v73, s[4:5]
	v_cndmask_b32_e64 v40, v40, v72, s[4:5]
	v_cndmask_b32_e64 v35, v35, v57, s[4:5]
	v_cndmask_b32_e64 v34, v34, v56, s[4:5]
	v_cndmask_b32_e64 v33, v33, v55, s[4:5]
	v_cndmask_b32_e64 v32, v32, v54, s[4:5]
	v_cndmask_b32_e64 v39, v39, v53, s[4:5]
	v_cndmask_b32_e64 v38, v38, v52, s[4:5]
	v_cndmask_b32_e64 v37, v37, v51, s[4:5]
	v_cndmask_b32_e64 v36, v36, v50, s[4:5]
	v_pk_mul_f32 v[46:47], v[128:129], v[46:47] op_sel_hi:[0,1]
	v_pk_mul_f32 v[44:45], v[128:129], v[44:45] op_sel_hi:[0,1]
	v_pk_mul_f32 v[42:43], v[128:129], v[42:43] op_sel_hi:[0,1]
	v_pk_mul_f32 v[40:41], v[128:129], v[40:41] op_sel_hi:[0,1]
	v_pk_mul_f32 v[50:51], v[128:129], v[34:35] op_sel_hi:[0,1]
	v_pk_mul_f32 v[52:53], v[128:129], v[32:33] op_sel_hi:[0,1]
	v_cvt_pk_bf16_f32 v32, v44, v45
	v_cvt_pk_bf16_f32 v33, v46, v47
	v_cvt_pk_bf16_f32 v34, v40, v41
	v_cvt_pk_bf16_f32 v35, v42, v43
	v_pk_mul_f32 v[38:39], v[128:129], v[38:39] op_sel_hi:[0,1]
	v_pk_mul_f32 v[36:37], v[128:129], v[36:37] op_sel_hi:[0,1]
	global_store_dwordx4 v[62:63], v[32:35], off
	ds_bpermute_b32 v54, v129, v28
	ds_bpermute_b32 v56, v129, v24
	v_cvt_pk_bf16_f32 v32, v36, v37
	v_cvt_pk_bf16_f32 v33, v38, v39
	v_cvt_pk_bf16_f32 v34, v52, v53
	v_cvt_pk_bf16_f32 v35, v50, v51
	global_store_dwordx4 v[62:63], v[32:35], off offset:256
	s_waitcnt vmcnt(10)
	s_nop 1
	v_mov_b32_e32 v32, v236
	v_mov_b32_e32 v33, v237
	v_mov_b32_e32 v34, v238
	v_mov_b32_e32 v35, v239
	v_mov_b32_e32 v36, v240
	v_mov_b32_e32 v37, v241
	v_mov_b32_e32 v38, v242
	v_mov_b32_e32 v39, v243
	v_mov_b32_e32 v40, v244
	v_mov_b32_e32 v41, v245
	v_mov_b32_e32 v42, v246
	v_mov_b32_e32 v43, v247
	v_mov_b32_e32 v44, v248
	v_mov_b32_e32 v45, v249
	v_mov_b32_e32 v46, v250
	v_mov_b32_e32 v47, v251
	ds_bpermute_b32 v55, v129, v29
	ds_bpermute_b32 v57, v129, v25
	ds_bpermute_b32 v58, v129, v30
	ds_bpermute_b32 v60, v129, v26
	ds_bpermute_b32 v59, v129, v31
	ds_bpermute_b32 v61, v129, v27
	ds_bpermute_b32 v64, v129, v16
	ds_bpermute_b32 v65, v129, v17
	ds_bpermute_b32 v68, v129, v18
	ds_bpermute_b32 v69, v129, v19
	ds_bpermute_b32 v62, v129, v20
	ds_bpermute_b32 v63, v129, v21
	ds_bpermute_b32 v66, v129, v22
	ds_bpermute_b32 v67, v129, v23
	v_add_u32_e32 v50, 0xb0, v154
	v_ashrrev_i32_e32 v51, 31, v50
	v_lshlrev_b64 v[52:53], 6, v[50:51]
	v_lshl_add_u64 v[52:53], s[20:21], 0, v[52:53]
	s_waitcnt lgkmcnt(9)
	v_pk_mul_f32 v[58:59], v[34:35], v[58:59]
	v_pk_mul_f32 v[54:55], v[32:33], v[54:55]
	s_waitcnt lgkmcnt(8)
	v_pk_mul_f32 v[60:61], v[38:39], v[60:61]
	v_pk_mul_f32 v[56:57], v[36:37], v[56:57]
	s_waitcnt lgkmcnt(4)
	v_pk_mul_f32 v[38:39], v[38:39], v[68:69]
	v_pk_mul_f32 v[36:37], v[36:37], v[64:65]
	s_waitcnt lgkmcnt(0)
; __device__ __forceinline__ unsigned cvt_pk_bf16(float lo, float hi) { unsigned r; asm volatile("v_cvt_pk_bf16_f32 %0, %1, %2" : "=v"(r) : "v"(lo), "v"(hi)); return r; }
;     __device__ __forceinline__ void operator()(const AccT& acc, const Unit& u, int wr, int wc, int fr, int fq) const {
;     ...
;                 for (int m = 0; m < 4; ++m) {
;                     const int row = u.pm * 256 + ai * 128 + wr * 64 + m * 16 + fr;
;                     const f32x4* rt = (const f32x4*)(ROT + (size_t)row * 16);
;                     const f32x4 c0 = rt[0], c1 = rt[1], s0 = rt[2], s1 = rt[3];
; #pragma unroll
;                     for (int bj = 0; bj < 2; ++bj) {
;                         const int col0 = colt + bj * 128 + wc * 32 + 8 * fq;
;                         f32x4 v0 = acc[ai][bj][m][0], v1 = acc[ai][bj][m][1];
;                         f32x4 p0, p1;
; #pragma unroll
;                         for (int e = 0; e < 4; ++e) { p0[e] = __shfl_xor(v0[e], 16); p1[e] = __shfl_xor(v1[e], 16); }
;                         const f32x4 r0 = v0 * c0 + sg * (p0 * s0), r1 = v1 * c1 + sg * (p1 * s1);
;                         v0 = rotl ? r0 : v0; v1 = rotl ? r1 : v1;
;                         v0 = v0 * qs; v1 = v1 * qs;
;                         u32x4 w; w.x = cvt_pk_bf16(v0[0], v0[1]); w.y = cvt_pk_bf16(v0[2], v0[3]); w.z = cvt_pk_bf16(v1[0], v1[1]); w.w = cvt_pk_bf16(v1[2], v1[3]);
;                         *(u32x4*)(PROJ + (size_t)row * PP + col0) = w;
;                     }
;                     if (m & 1) asm volatile("" ::: "memory");
;                 }
	v_pk_mul_f32 v[34:35], v[34:35], v[66:67]
	v_pk_mul_f32 v[32:33], v[32:33], v[62:63]
	v_pk_mul_f32 v[54:55], v[144:145], v[54:55]
	v_pk_mul_f32 v[58:59], v[146:147], v[58:59]
	v_pk_mul_f32 v[56:57], v[144:145], v[56:57]
	v_pk_mul_f32 v[60:61], v[146:147], v[60:61]
	v_pk_mul_f32 v[36:37], v[144:145], v[36:37]
	v_pk_mul_f32 v[38:39], v[146:147], v[38:39]
	v_pk_mul_f32 v[32:33], v[144:145], v[32:33]
	v_pk_mul_f32 v[34:35], v[146:147], v[34:35]
	v_pk_fma_f32 v[58:59], v[30:31], v[42:43], v[58:59]
	v_pk_fma_f32 v[54:55], v[28:29], v[40:41], v[54:55]
	v_pk_fma_f32 v[60:61], v[26:27], v[46:47], v[60:61]
	v_pk_fma_f32 v[56:57], v[24:25], v[44:45], v[56:57]
	v_pk_fma_f32 v[38:39], v[18:19], v[46:47], v[38:39]
	v_pk_fma_f32 v[36:37], v[16:17], v[44:45], v[36:37]
	v_pk_fma_f32 v[34:35], v[22:23], v[42:43], v[34:35]
	v_pk_fma_f32 v[32:33], v[20:21], v[40:41], v[32:33]
	v_cndmask_b32_e64 v31, v31, v59, s[4:5]
	v_cndmask_b32_e64 v30, v30, v58, s[4:5]
	v_cndmask_b32_e64 v29, v29, v55, s[4:5]
	v_cndmask_b32_e64 v28, v28, v54, s[4:5]
	v_cndmask_b32_e64 v27, v27, v61, s[4:5]
	v_cndmask_b32_e64 v26, v26, v60, s[4:5]
	v_cndmask_b32_e64 v25, v25, v57, s[4:5]
	v_cndmask_b32_e64 v24, v24, v56, s[4:5]
	v_cndmask_b32_e64 v19, v19, v39, s[4:5]
	v_cndmask_b32_e64 v18, v18, v38, s[4:5]
	v_cndmask_b32_e64 v17, v17, v37, s[4:5]
	v_cndmask_b32_e64 v16, v16, v36, s[4:5]
	v_cndmask_b32_e64 v23, v23, v35, s[4:5]
	v_cndmask_b32_e64 v22, v22, v34, s[4:5]
	v_cndmask_b32_e64 v21, v21, v33, s[4:5]
	v_cndmask_b32_e64 v20, v20, v32, s[4:5]
	v_pk_mul_f32 v[30:31], v[128:129], v[30:31] op_sel_hi:[0,1]
	v_pk_mul_f32 v[28:29], v[128:129], v[28:29] op_sel_hi:[0,1]
	v_pk_mul_f32 v[26:27], v[128:129], v[26:27] op_sel_hi:[0,1]
	v_pk_mul_f32 v[24:25], v[128:129], v[24:25] op_sel_hi:[0,1]
	v_pk_mul_f32 v[32:33], v[128:129], v[18:19] op_sel_hi:[0,1]
	v_pk_mul_f32 v[34:35], v[128:129], v[16:17] op_sel_hi:[0,1]
	v_cvt_pk_bf16_f32 v16, v28, v29
	v_cvt_pk_bf16_f32 v17, v30, v31
	v_cvt_pk_bf16_f32 v18, v24, v25
	v_cvt_pk_bf16_f32 v19, v26, v27
	v_pk_mul_f32 v[22:23], v[128:129], v[22:23] op_sel_hi:[0,1]
	v_pk_mul_f32 v[20:21], v[128:129], v[20:21] op_sel_hi:[0,1]
	global_store_dwordx4 v[48:49], v[16:19], off
	ds_bpermute_b32 v36, v129, v8
	ds_bpermute_b32 v37, v129, v9
	v_cvt_pk_bf16_f32 v16, v20, v21
	v_cvt_pk_bf16_f32 v17, v22, v23
	v_cvt_pk_bf16_f32 v18, v34, v35
	v_cvt_pk_bf16_f32 v19, v32, v33
	global_store_dwordx4 v[48:49], v[16:19], off offset:256
	s_waitcnt vmcnt(6)
	s_nop 1
	v_mov_b32_e32 v16, v196
	v_mov_b32_e32 v17, v197
	v_mov_b32_e32 v18, v198
	v_mov_b32_e32 v19, v199
	v_mov_b32_e32 v20, v200
	v_mov_b32_e32 v21, v201
	v_mov_b32_e32 v22, v202
	v_mov_b32_e32 v23, v203
	v_mov_b32_e32 v24, v204
	v_mov_b32_e32 v25, v205
	v_mov_b32_e32 v26, v206
	v_mov_b32_e32 v27, v207
	v_mov_b32_e32 v28, v208
	v_mov_b32_e32 v29, v209
	v_mov_b32_e32 v30, v210
	v_mov_b32_e32 v31, v211
	s_nop 0
	ds_bpermute_b32 v34, v129, v12
	ds_bpermute_b32 v35, v129, v13
	ds_bpermute_b32 v38, v129, v14
	ds_bpermute_b32 v40, v129, v10
	ds_bpermute_b32 v39, v129, v15
	ds_bpermute_b32 v41, v129, v11
	ds_bpermute_b32 v44, v129, v0
	ds_bpermute_b32 v45, v129, v1
	ds_bpermute_b32 v48, v129, v2
	ds_bpermute_b32 v49, v129, v3
	ds_bpermute_b32 v42, v129, v4
	ds_bpermute_b32 v43, v129, v5
	ds_bpermute_b32 v46, v129, v6
	ds_bpermute_b32 v47, v129, v7
	v_mad_i64_i32 v[32:33], s[8:9], v50, s52, v[130:131]
	v_lshl_add_u64 v[32:33], v[32:33], 0, v[152:153]
	s_waitcnt lgkmcnt(9)
	v_pk_mul_f32 v[38:39], v[18:19], v[38:39]
	v_pk_mul_f32 v[34:35], v[16:17], v[34:35]
	s_waitcnt lgkmcnt(8)
	v_pk_mul_f32 v[40:41], v[22:23], v[40:41]
	v_pk_mul_f32 v[36:37], v[20:21], v[36:37]
	s_waitcnt lgkmcnt(4)
	v_pk_mul_f32 v[22:23], v[22:23], v[48:49]
	v_pk_mul_f32 v[20:21], v[20:21], v[44:45]
	s_waitcnt lgkmcnt(0)
	v_pk_mul_f32 v[18:19], v[18:19], v[46:47]
	v_pk_mul_f32 v[16:17], v[16:17], v[42:43]
	v_pk_mul_f32 v[34:35], v[144:145], v[34:35]
	v_pk_mul_f32 v[38:39], v[146:147], v[38:39]
	v_pk_mul_f32 v[36:37], v[144:145], v[36:37]
	v_pk_mul_f32 v[40:41], v[146:147], v[40:41]
	v_pk_mul_f32 v[20:21], v[144:145], v[20:21]
	v_pk_mul_f32 v[22:23], v[146:147], v[22:23]
	v_pk_mul_f32 v[16:17], v[144:145], v[16:17]
	v_pk_mul_f32 v[18:19], v[146:147], v[18:19]
	v_pk_fma_f32 v[38:39], v[14:15], v[26:27], v[38:39]
	v_pk_fma_f32 v[34:35], v[12:13], v[24:25], v[34:35]
	v_pk_fma_f32 v[40:41], v[10:11], v[30:31], v[40:41]
	v_pk_fma_f32 v[36:37], v[8:9], v[28:29], v[36:37]
	v_pk_fma_f32 v[22:23], v[2:3], v[30:31], v[22:23]
	v_pk_fma_f32 v[20:21], v[0:1], v[28:29], v[20:21]
	v_pk_fma_f32 v[18:19], v[6:7], v[26:27], v[18:19]
	v_pk_fma_f32 v[16:17], v[4:5], v[24:25], v[16:17]
	v_cndmask_b32_e64 v15, v15, v39, s[4:5]
	v_cndmask_b32_e64 v14, v14, v38, s[4:5]
	v_cndmask_b32_e64 v13, v13, v35, s[4:5]
	v_cndmask_b32_e64 v12, v12, v34, s[4:5]
	v_cndmask_b32_e64 v11, v11, v41, s[4:5]
	v_cndmask_b32_e64 v10, v10, v40, s[4:5]
	v_cndmask_b32_e64 v9, v9, v37, s[4:5]
	v_cndmask_b32_e64 v8, v8, v36, s[4:5]
	v_cndmask_b32_e64 v3, v3, v23, s[4:5]
	v_cndmask_b32_e64 v2, v2, v22, s[4:5]
	v_cndmask_b32_e64 v1, v1, v21, s[4:5]
	v_cndmask_b32_e64 v0, v0, v20, s[4:5]
	v_cndmask_b32_e64 v7, v7, v19, s[4:5]
	v_cndmask_b32_e64 v6, v6, v18, s[4:5]
	v_cndmask_b32_e64 v5, v5, v17, s[4:5]
	v_cndmask_b32_e64 v4, v4, v16, s[4:5]
	v_pk_mul_f32 v[14:15], v[128:129], v[14:15] op_sel_hi:[0,1]
	v_pk_mul_f32 v[12:13], v[128:129], v[12:13] op_sel_hi:[0,1]
	v_pk_mul_f32 v[10:11], v[128:129], v[10:11] op_sel_hi:[0,1]
	v_pk_mul_f32 v[8:9], v[128:129], v[8:9] op_sel_hi:[0,1]
	v_pk_mul_f32 v[16:17], v[128:129], v[2:3] op_sel_hi:[0,1]
	v_pk_mul_f32 v[18:19], v[128:129], v[0:1] op_sel_hi:[0,1]
	v_cvt_pk_bf16_f32 v0, v12, v13
	v_cvt_pk_bf16_f32 v1, v14, v15
	v_cvt_pk_bf16_f32 v2, v8, v9
	v_cvt_pk_bf16_f32 v3, v10, v11
	v_pk_mul_f32 v[6:7], v[128:129], v[6:7] op_sel_hi:[0,1]
	v_pk_mul_f32 v[4:5], v[128:129], v[4:5] op_sel_hi:[0,1]
	global_store_dwordx4 v[32:33], v[0:3], off
	s_nop 1
	v_cvt_pk_bf16_f32 v0, v4, v5
	v_cvt_pk_bf16_f32 v1, v6, v7
	v_cvt_pk_bf16_f32 v2, v18, v19
	v_cvt_pk_bf16_f32 v3, v16, v17
	global_store_dwordx4 v[32:33], v[0:3], off offset:256
	s_andn2_b64 vcc, exec, s[6:7]
	s_mov_b64 s[6:7], -1
	s_cbranch_vccnz .LBB0_250
